# QK^T K-fragment reads software-pipelined 4-8 deep in MLA attention loop (bit-identical)
# speedup vs baseline: 1.0009x; 1.0009x over previous
.LBB0_148:
	s_add_i32 s36, s57, -2
	s_and_b32 s74, s36, 1
	s_lshl_b32 s36, s74, 14
	s_lshl_b32 s42, s74, 13
	s_add_i32 s42, s42, 0x14000
	v_add3_u32 v210, s36, v222, v221
	v_add3_u32 v211, s36, v223, v221
	v_add3_u32 v212, s36, v224, v221
	v_add3_u32 v213, s36, v225, v221
	ds_read_b128 v[240:243], v210 offset:49152
	ds_read_b128 v[244:247], v211 offset:49152
	ds_read_b128 v[248:251], v212 offset:49152
	ds_read_b128 v[236:239], v213 offset:49152
	ds_read_b128 v[64:67], v210 offset:49280
	ds_read_b128 v[68:71], v211 offset:49280
	ds_read_b128 v[72:75], v212 offset:49280
	ds_read_b128 v[76:79], v213 offset:49280
	v_add3_u32 v234, s42, v227, v226
	v_add3_u32 v235, s42, v228, v226
	s_waitcnt lgkmcnt(7)
	v_mfma_f32_32x32x16_bf16 v[80:95], v[240:243], v[98:101], 0
	ds_read_b128 v[240:243], v234
	s_waitcnt lgkmcnt(7)
	v_mfma_f32_32x32x16_bf16 v[80:95], v[244:247], v[102:105], v[80:95]
	ds_read_b128 v[244:247], v235
	v_add3_u32 v234, s42, v229, v226
	v_add3_u32 v235, s42, v230, v226
	s_waitcnt lgkmcnt(7)
	v_mfma_f32_32x32x16_bf16 v[80:95], v[248:251], v[106:109], v[80:95]
	ds_read_b128 v[248:251], v234
	s_waitcnt lgkmcnt(7)
	v_mfma_f32_32x32x16_bf16 v[80:95], v[236:239], v[110:113], v[80:95]
	ds_read_b128 v[236:239], v235
	s_waitcnt lgkmcnt(7)
	v_mfma_f32_32x32x16_bf16 v[80:95], v[64:67], v[114:117], v[80:95]
	ds_read_b128 v[64:67], v210 offset:57344
	s_waitcnt lgkmcnt(7)
	v_mfma_f32_32x32x16_bf16 v[80:95], v[68:71], v[118:121], v[80:95]
	s_waitcnt lgkmcnt(6)
	v_mfma_f32_32x32x16_bf16 v[80:95], v[72:75], v[122:125], v[80:95]
	s_waitcnt lgkmcnt(5)
	v_mfma_f32_32x32x16_bf16 v[80:95], v[76:79], v[126:129], v[80:95]
	s_waitcnt lgkmcnt(4)
	v_mfma_f32_32x32x16_bf16 v[80:95], v[240:243], v[130:133], v[80:95]
	ds_read_b128 v[240:243], v211 offset:57344
	s_waitcnt lgkmcnt(4)
	v_mfma_f32_32x32x16_bf16 v[80:95], v[244:247], v[138:141], v[80:95]
	ds_read_b128 v[244:247], v212 offset:57344
	s_waitcnt lgkmcnt(4)
	v_mfma_f32_32x32x16_bf16 v[80:95], v[248:251], v[134:137], v[80:95]
	ds_read_b128 v[248:251], v213 offset:57344
	s_waitcnt lgkmcnt(4)
	v_mfma_f32_32x32x16_bf16 v[80:95], v[236:239], v[142:145], v[80:95]
	ds_read_b128 v[236:239], v210 offset:57472
	s_waitcnt lgkmcnt(4)
	v_mfma_f32_32x32x16_bf16 v[64:79], v[64:67], v[98:101], 0
	s_waitcnt lgkmcnt(3)
	v_mfma_f32_32x32x16_bf16 v[64:79], v[240:243], v[102:105], v[64:79]
	ds_read_b128 v[240:243], v211 offset:57472
	s_waitcnt lgkmcnt(3)
	v_mfma_f32_32x32x16_bf16 v[64:79], v[244:247], v[106:109], v[64:79]
	ds_read_b128 v[244:247], v212 offset:57472
	v_add3_u32 v210, s42, v227, v226
	s_waitcnt lgkmcnt(3)
	v_mfma_f32_32x32x16_bf16 v[64:79], v[248:251], v[110:113], v[64:79]
	ds_read_b128 v[248:251], v213 offset:57472
	v_add3_u32 v211, s42, v228, v226
	s_waitcnt lgkmcnt(3)
	v_mfma_f32_32x32x16_bf16 v[64:79], v[236:239], v[114:117], v[64:79]
	ds_read_b128 v[236:239], v210 offset:4096
	v_add3_u32 v212, s42, v229, v226
	s_waitcnt lgkmcnt(3)
	v_mfma_f32_32x32x16_bf16 v[64:79], v[240:243], v[118:121], v[64:79]
	ds_read_b128 v[240:243], v211 offset:4096
	v_add3_u32 v213, s42, v230, v226
	s_waitcnt lgkmcnt(3)
	v_mfma_f32_32x32x16_bf16 v[64:79], v[244:247], v[122:125], v[64:79]
	ds_read_b128 v[244:247], v212 offset:4096
	s_waitcnt lgkmcnt(3)
	v_mfma_f32_32x32x16_bf16 v[64:79], v[248:251], v[126:129], v[64:79]
	ds_read_b128 v[248:251], v213 offset:4096
	s_waitcnt lgkmcnt(3)
	v_mfma_f32_32x32x16_bf16 v[64:79], v[236:239], v[130:133], v[64:79]
	s_waitcnt lgkmcnt(2)
	v_mfma_f32_32x32x16_bf16 v[64:79], v[240:243], v[138:141], v[64:79]
	s_waitcnt lgkmcnt(1)
	v_mfma_f32_32x32x16_bf16 v[64:79], v[244:247], v[134:137], v[64:79]
	s_waitcnt lgkmcnt(0)
	v_mfma_f32_32x32x16_bf16 v[64:79], v[248:251], v[142:145], v[64:79]
	s_add_i32 s36, s8, 63
	s_cmp_le_i32 s36, s2
	s_cselect_b64 s[36:37], -1, 0
	s_cmp_gt_i32 s8, s55
	s_cselect_b64 s[42:43], -1, 0
	s_and_b64 s[36:37], s[36:37], s[42:43]
	s_and_b64 vcc, exec, s[36:37]
	s_cbranch_vccnz .LBB0_150
	v_add_u32_e32 v210, s69, v231
	v_cmp_gt_u32_e32 vcc, s66, v210
	v_add_u32_e32 v211, 0xffefffe0, v210
	s_nop 0
	v_cndmask_b32_e32 v80, v214, v80, vcc
	v_cmp_lt_u32_e32 vcc, s67, v211
	v_add_u32_e32 v211, 0xffefffff, v210
	s_nop 0
	v_cndmask_b32_e32 v64, v214, v64, vcc
	v_cmp_lt_u32_e32 vcc, s67, v211
	v_add_u32_e32 v211, 0xffefffdf, v210
	s_nop 0
	v_cndmask_b32_e32 v81, v214, v81, vcc
	v_cmp_lt_u32_e32 vcc, s67, v211
	v_add_u32_e32 v211, 0xffeffffe, v210
	s_nop 0
	v_cndmask_b32_e32 v65, v214, v65, vcc
	v_cmp_lt_u32_e32 vcc, s67, v211
	v_add_u32_e32 v211, 0xffefffde, v210
	s_nop 0
	v_cndmask_b32_e32 v82, v214, v82, vcc
	v_cmp_lt_u32_e32 vcc, s67, v211
	v_add_u32_e32 v211, 0xffeffffd, v210
	s_nop 0
	v_cndmask_b32_e32 v66, v214, v66, vcc
	v_cmp_lt_u32_e32 vcc, s67, v211
	v_add_u32_e32 v211, 0xffefffdd, v210
	s_nop 0
	v_cndmask_b32_e32 v83, v214, v83, vcc
	v_cmp_lt_u32_e32 vcc, s67, v211
	v_add_u32_e32 v211, 0xffeffff8, v210
	s_nop 0
	v_cndmask_b32_e32 v67, v214, v67, vcc
	v_cmp_lt_u32_e32 vcc, s67, v211
	v_add_u32_e32 v211, 0xffefffd8, v210
	s_nop 0
	v_cndmask_b32_e32 v84, v214, v84, vcc
	v_cmp_lt_u32_e32 vcc, s67, v211
	v_add_u32_e32 v211, 0xffeffff7, v210
	s_nop 0
	v_cndmask_b32_e32 v68, v214, v68, vcc
	v_cmp_lt_u32_e32 vcc, s67, v211
	v_add_u32_e32 v211, 0xffefffd7, v210
	s_nop 0
	v_cndmask_b32_e32 v85, v214, v85, vcc
	v_cmp_lt_u32_e32 vcc, s67, v211
	v_add_u32_e32 v211, 0xffeffff6, v210
	s_nop 0
	v_cndmask_b32_e32 v69, v214, v69, vcc
	v_cmp_lt_u32_e32 vcc, s67, v211
	v_add_u32_e32 v211, 0xffefffd6, v210
	s_nop 0
	v_cndmask_b32_e32 v86, v214, v86, vcc
	v_cmp_lt_u32_e32 vcc, s67, v211
	v_add_u32_e32 v211, 0xffeffff5, v210
	s_nop 0
	v_cndmask_b32_e32 v70, v214, v70, vcc
	v_cmp_lt_u32_e32 vcc, s67, v211
	v_add_u32_e32 v211, 0xffefffd5, v210
	s_nop 0
	v_cndmask_b32_e32 v87, v214, v87, vcc
	v_cmp_lt_u32_e32 vcc, s67, v211
	v_add_u32_e32 v211, 0xffeffff0, v210
	s_nop 0
	v_cndmask_b32_e32 v71, v214, v71, vcc
	v_cmp_lt_u32_e32 vcc, s67, v211
	v_add_u32_e32 v211, 0xffefffd0, v210
	s_nop 0
	v_cndmask_b32_e32 v88, v214, v88, vcc
	v_cmp_lt_u32_e32 vcc, s67, v211
	v_add_u32_e32 v211, 0xffefffef, v210
	s_nop 0
	v_cndmask_b32_e32 v72, v214, v72, vcc
	v_cmp_lt_u32_e32 vcc, s67, v211
	v_add_u32_e32 v211, 0xffefffcf, v210
	s_nop 0
	v_cndmask_b32_e32 v89, v214, v89, vcc
	v_cmp_lt_u32_e32 vcc, s67, v211
	v_add_u32_e32 v211, 0xffefffee, v210
	s_nop 0
	v_cndmask_b32_e32 v73, v214, v73, vcc
	v_cmp_lt_u32_e32 vcc, s67, v211
	v_add_u32_e32 v211, 0xffefffce, v210
	s_nop 0
	v_cndmask_b32_e32 v90, v214, v90, vcc
	v_cmp_lt_u32_e32 vcc, s67, v211
	v_add_u32_e32 v211, 0xffefffed, v210
	s_nop 0
	v_cndmask_b32_e32 v74, v214, v74, vcc
	v_cmp_lt_u32_e32 vcc, s67, v211
	v_add_u32_e32 v211, 0xffefffcd, v210
	s_nop 0
	v_cndmask_b32_e32 v91, v214, v91, vcc
	v_cmp_lt_u32_e32 vcc, s67, v211
	v_add_u32_e32 v211, 0xffefffe8, v210
	s_nop 0
	v_cndmask_b32_e32 v75, v214, v75, vcc
	v_cmp_lt_u32_e32 vcc, s67, v211
	v_add_u32_e32 v211, 0xffefffc8, v210
	s_nop 0
	v_cndmask_b32_e32 v92, v214, v92, vcc
	v_cmp_lt_u32_e32 vcc, s67, v211
	v_add_u32_e32 v211, 0xffefffe7, v210
	s_nop 0
	v_cndmask_b32_e32 v76, v214, v76, vcc
	v_cmp_lt_u32_e32 vcc, s67, v211
	v_add_u32_e32 v211, 0xffefffc7, v210
	s_nop 0
	v_cndmask_b32_e32 v93, v214, v93, vcc
	v_cmp_lt_u32_e32 vcc, s67, v211
	v_add_u32_e32 v211, 0xffefffe6, v210
	s_nop 0
	v_cndmask_b32_e32 v77, v214, v77, vcc
	v_cmp_lt_u32_e32 vcc, s67, v211
	v_add_u32_e32 v211, 0xffefffc6, v210
	s_nop 0
	v_cndmask_b32_e32 v94, v214, v94, vcc
	v_cmp_lt_u32_e32 vcc, s67, v211
	v_add_u32_e32 v211, 0xffefffe5, v210
	v_add_u32_e32 v210, 0xffefffc5, v210
	v_cndmask_b32_e32 v78, v214, v78, vcc
	v_cmp_lt_u32_e32 vcc, s67, v211
	s_nop 1
	v_cndmask_b32_e32 v95, v214, v95, vcc
	v_cmp_lt_u32_e32 vcc, s67, v210
	s_nop 1
	v_cndmask_b32_e32 v79, v214, v79, vcc
